# phase-0 row conversion loops: four row-segment loads issued together (was load-wait x4 per row)
# speedup vs baseline: 1.0084x; 1.0030x over previous
.LBB0_2006:
	global_load_dwordx4 v[18:21], v[8:9], off offset:-2048
	global_load_dwordx4 v[22:25], v[8:9], off offset:-1024
	global_load_dwordx4 v[26:29], v[8:9], off
	global_load_dwordx4 v[30:33], v[8:9], off offset:1024
	s_waitcnt vmcnt(0)
	v_cvt_pk_bf16_f32 v40, v18, v19
	v_cvt_pk_bf16_f32 v41, v20, v21
	global_store_dwordx2 v[6:7], v[40:41], off offset:-1024
	v_mul_f32_e32 v3, v19, v19
	s_waitcnt lgkmcnt(0)
	v_mul_f32_e32 v17, v21, v21
	v_fmac_f32_e32 v3, v18, v18
	v_fmac_f32_e32 v17, v20, v20
	v_add_f32_e32 v3, v3, v17
	v_cvt_pk_bf16_f32 v40, v22, v23
	v_cvt_pk_bf16_f32 v41, v24, v25
	global_store_dwordx2 v[6:7], v[40:41], off offset:-512
	v_mul_f32_e32 v17, v23, v23
	v_mul_f32_e32 v18, v25, v25
	v_fmac_f32_e32 v17, v22, v22
	v_fmac_f32_e32 v18, v24, v24
	v_add_f32_e32 v17, v17, v18
	v_add_f32_e32 v3, v3, v17
	v_cvt_pk_bf16_f32 v40, v26, v27
	v_cvt_pk_bf16_f32 v41, v28, v29
	global_store_dwordx2 v[6:7], v[40:41], off
	v_mul_f32_e32 v17, v27, v27
	v_mul_f32_e32 v18, v29, v29
	v_fmac_f32_e32 v17, v26, v26
	v_fmac_f32_e32 v18, v28, v28
	v_add_f32_e32 v17, v17, v18
	v_add_f32_e32 v3, v3, v17
	v_mul_f32_e32 v17, v31, v31
	v_mul_f32_e32 v18, v33, v33
	v_fmac_f32_e32 v17, v30, v30
	v_fmac_f32_e32 v18, v32, v32
	v_add_f32_e32 v17, v17, v18
	v_add_f32_e32 v3, v3, v17
	ds_bpermute_b32 v17, v11, v3
	v_cvt_pk_bf16_f32 v18, v30, v31
	v_cvt_pk_bf16_f32 v19, v32, v33
	global_store_dwordx2 v[6:7], v[18:19], off offset:512
	s_waitcnt lgkmcnt(0)
	v_add_f32_e32 v3, v3, v17
	ds_bpermute_b32 v17, v12, v3
	s_waitcnt lgkmcnt(0)
	v_add_f32_e32 v3, v3, v17
	ds_bpermute_b32 v17, v13, v3
	s_waitcnt lgkmcnt(0)
	v_add_f32_e32 v3, v3, v17
	ds_bpermute_b32 v17, v14, v3
	s_waitcnt lgkmcnt(0)
	v_add_f32_e32 v3, v3, v17
	ds_bpermute_b32 v17, v15, v3
	s_waitcnt lgkmcnt(0)
	v_add_f32_e32 v3, v3, v17
	ds_bpermute_b32 v17, v16, v3
	s_and_saveexec_b64 s[8:9], vcc
	s_cbranch_execz .LBB0_2005
	s_waitcnt lgkmcnt(0)
	v_add_f32_e32 v3, v3, v17
	v_cndmask_b32_e64 v3, 0, v3, s[6:7]
	global_store_dword v[4:5], v3, off
	s_branch .LBB0_2005

.LBB0_2011:
	global_load_dwordx4 v[16:19], v[8:9], off offset:-2048
	global_load_dwordx4 v[20:23], v[8:9], off offset:-1024
	global_load_dwordx4 v[24:27], v[8:9], off
	global_load_dwordx4 v[28:31], v[8:9], off offset:1024
	s_waitcnt vmcnt(0)
	v_cvt_pk_bf16_f32 v40, v16, v17
	v_cvt_pk_bf16_f32 v41, v18, v19
	global_store_dwordx2 v[6:7], v[40:41], off offset:-1024
	v_mul_f32_e32 v1, v17, v17
	s_waitcnt lgkmcnt(0)
	v_mul_f32_e32 v3, v19, v19
	v_fmac_f32_e32 v1, v16, v16
	v_fmac_f32_e32 v3, v18, v18
	v_add_f32_e32 v1, v1, v3
	v_cvt_pk_bf16_f32 v40, v20, v21
	v_cvt_pk_bf16_f32 v41, v22, v23
	global_store_dwordx2 v[6:7], v[40:41], off offset:-512
	v_mul_f32_e32 v3, v21, v21
	v_mul_f32_e32 v16, v23, v23
	v_fmac_f32_e32 v3, v20, v20
	v_fmac_f32_e32 v16, v22, v22
	v_add_f32_e32 v3, v3, v16
	v_add_f32_e32 v1, v1, v3
	v_cvt_pk_bf16_f32 v40, v24, v25
	v_cvt_pk_bf16_f32 v41, v26, v27
	global_store_dwordx2 v[6:7], v[40:41], off
	v_mul_f32_e32 v3, v25, v25
	v_mul_f32_e32 v16, v27, v27
	v_fmac_f32_e32 v3, v24, v24
	v_fmac_f32_e32 v16, v26, v26
	v_add_f32_e32 v3, v3, v16
	v_add_f32_e32 v1, v1, v3
	v_mul_f32_e32 v3, v29, v29
	v_mul_f32_e32 v16, v31, v31
	v_fmac_f32_e32 v3, v28, v28
	v_fmac_f32_e32 v16, v30, v30
	v_add_f32_e32 v3, v3, v16
	v_add_f32_e32 v1, v1, v3
	ds_bpermute_b32 v3, v10, v1
	v_cvt_pk_bf16_f32 v16, v28, v29
	v_cvt_pk_bf16_f32 v17, v30, v31
	global_store_dwordx2 v[6:7], v[16:17], off offset:512
	s_waitcnt lgkmcnt(0)
	v_add_f32_e32 v1, v1, v3
	ds_bpermute_b32 v3, v11, v1
	s_waitcnt lgkmcnt(0)
	v_add_f32_e32 v1, v1, v3
	ds_bpermute_b32 v3, v12, v1
	s_waitcnt lgkmcnt(0)
	v_add_f32_e32 v1, v1, v3
	ds_bpermute_b32 v3, v13, v1
	s_waitcnt lgkmcnt(0)
	v_add_f32_e32 v1, v1, v3
	ds_bpermute_b32 v3, v14, v1
	s_waitcnt lgkmcnt(0)
	v_add_f32_e32 v1, v1, v3
	ds_bpermute_b32 v3, v15, v1
	s_and_saveexec_b64 s[8:9], vcc
	s_cbranch_execz .LBB0_2010
	s_waitcnt lgkmcnt(0)
	v_add_f32_e32 v1, v1, v3
	v_cndmask_b32_e64 v1, 0, v1, s[6:7]
	global_store_dword v[4:5], v1, off
	s_branch .LBB0_2010
